# P6 EpiAct SS1 hoist + P1 EpiIn PB/FZ tile stores routed through wave-private LDS transposition (coalesced row stores)
# baseline (speedup 1.0000x reference)
;     __device__ __forceinline__ void operator()(const pg8::f32x4 (&acc)[2][2][4][2], const Unit& u, int wr, int wc, int fr, int fq) const {
;     ...
;         } else { const int col0 = (u.pn - 8) * BM + wc * 32 + 8 * fq;
; #pragma unroll
;             for (int ai = 0; ai < 2; ++ai)
; #pragma unroll
;                 for (int m = 0; m < 4; ++m) { float* rowp = FZ + (size_t)(row0 + ai * HALF + m * 16) * 512 + col0;
; #pragma unroll
;                     for (int bj = 0; bj < 2; ++bj)
; #pragma unroll
;                         for (int n = 0; n < 2; ++n) *(pg8::f32x4*)(rowp + bj * HALF + 4 * n) = acc[ai][bj][m][n]; }
;         }
.LBB0_140:
	v_lshl_add_u32 v150, s20, 8, v156
	s_cmp_gt_i32 s44, 1
	v_ashrrev_i32_e32 v151, 31, v150
	s_mov_b64 s[20:21], -1
	s_cbranch_scc0 .LBB0_147
	s_lshl_b32 s13, s44, 8
	s_cmp_gt_u32 s44, 7
	s_cbranch_scc0 .LBB0_143
	v_readlane_b32 s20, v238, 45
	v_readlane_b32 s21, v238, 46
	v_add_u32_e32 v138, s13, v159
	v_lshlrev_b64 v[152:153], 11, v[150:151]
	v_lshlrev_b64 v[164:165], 2, v[138:139]
	v_lshl_add_u64 v[152:153], s[20:21], 0, v[152:153]
	v_lshl_add_u64 v[152:153], v[152:153], 0, v[164:165]
	v_and_b32_e32 v164, 63, v0
	v_and_b32_e32 v165, 15, v164
	v_lshrrev_b32_e32 v166, 4, v164
	v_lshrrev_b32_e32 v169, 6, v0
	v_lshlrev_b32_e32 v169, 11, v169
	v_add_u32_e32 v169, 0x20000, v169
	v_lshrrev_b32_e32 v167, 3, v164
	v_and_b32_e32 v168, 7, v164
	v_and_b32_e32 v170, 7, v165
	v_lshlrev_b32_e32 v171, 1, v166
	v_xor_b32_e32 v170, v170, v171
	v_lshlrev_b32_e32 v170, 4, v170
	v_lshl_add_u32 v170, v165, 7, v170
	v_add_u32_e32 v170, v169, v170
	v_xor_b32_e32 v171, 16, v170
	v_xor_b32_e32 v172, v167, v168
	v_lshlrev_b32_e32 v172, 4, v172
	v_lshl_add_u32 v172, v167, 7, v172
	v_add_u32_e32 v172, v169, v172
	v_sub_u32_e32 v174, v167, v165
	v_lshlrev_b32_e32 v174, 11, v174
	v_lshlrev_b32_e32 v169, 1, v166
	v_sub_u32_e32 v169, v168, v169
	v_lshl_add_u32 v174, v169, 4, v174
	v_ashrrev_i32_e32 v175, 31, v174
	v_lshl_add_u64 v[174:175], v[152:153], 0, v[174:175]
	s_mov_b64 s[20:21], 0x4000
	v_lshl_add_u64 v[200:201], v[174:175], 0, s[20:21]
	s_mov_b64 s[20:21], 0x8000
	ds_write_b128 v170, v[126:129]
	ds_write_b128 v171, v[122:125]
	ds_read_b128 v[184:187], v172
	ds_read_b128 v[188:191], v172 offset:1024
	ds_write_b128 v170, v[118:121]
	ds_write_b128 v171, v[110:113]
	ds_read_b128 v[192:195], v172
	ds_read_b128 v[196:199], v172 offset:1024
	s_waitcnt lgkmcnt(4)
	global_store_dwordx4 v[174:175], v[184:187], off
	global_store_dwordx4 v[200:201], v[188:191], off
	ds_write_b128 v170, v[114:117]
	ds_write_b128 v171, v[106:109]
	ds_read_b128 v[184:187], v172
	ds_read_b128 v[188:191], v172 offset:1024
	s_waitcnt lgkmcnt(4)
	global_store_dwordx4 v[174:175], v[192:195], off offset:512
	global_store_dwordx4 v[200:201], v[196:199], off offset:512
	v_lshl_add_u64 v[174:175], v[174:175], 0, s[20:21]
	v_lshl_add_u64 v[200:201], v[200:201], 0, s[20:21]
	ds_write_b128 v170, v[98:101]
	ds_write_b128 v171, v[90:93]
	ds_read_b128 v[192:195], v172
	ds_read_b128 v[196:199], v172 offset:1024
	s_waitcnt lgkmcnt(4)
	global_store_dwordx4 v[174:175], v[184:187], off
	global_store_dwordx4 v[200:201], v[188:191], off
	ds_write_b128 v170, v[102:105]
	ds_write_b128 v171, v[94:97]
	ds_read_b128 v[184:187], v172
	ds_read_b128 v[188:191], v172 offset:1024
	s_waitcnt lgkmcnt(4)
	global_store_dwordx4 v[174:175], v[192:195], off offset:512
	global_store_dwordx4 v[200:201], v[196:199], off offset:512
	v_lshl_add_u64 v[174:175], v[174:175], 0, s[20:21]
	v_lshl_add_u64 v[200:201], v[200:201], 0, s[20:21]
	ds_write_b128 v170, v[82:85]
	ds_write_b128 v171, v[74:77]
	ds_read_b128 v[192:195], v172
	ds_read_b128 v[196:199], v172 offset:1024
	s_waitcnt lgkmcnt(4)
	global_store_dwordx4 v[174:175], v[184:187], off
	global_store_dwordx4 v[200:201], v[188:191], off
	ds_write_b128 v170, v[86:89]
	ds_write_b128 v171, v[78:81]
	ds_read_b128 v[184:187], v172
	ds_read_b128 v[188:191], v172 offset:1024
	s_waitcnt lgkmcnt(4)
	global_store_dwordx4 v[174:175], v[192:195], off offset:512
	global_store_dwordx4 v[200:201], v[196:199], off offset:512
	v_lshl_add_u64 v[174:175], v[174:175], 0, s[20:21]
	v_lshl_add_u64 v[200:201], v[200:201], 0, s[20:21]
	ds_write_b128 v170, v[70:73]
	ds_write_b128 v171, v[66:69]
	ds_read_b128 v[192:195], v172
	ds_read_b128 v[196:199], v172 offset:1024
	s_waitcnt lgkmcnt(4)
	global_store_dwordx4 v[174:175], v[184:187], off
	global_store_dwordx4 v[200:201], v[188:191], off
	ds_write_b128 v170, v[62:65]
	ds_write_b128 v171, v[58:61]
	ds_read_b128 v[184:187], v172
	ds_read_b128 v[188:191], v172 offset:1024
	s_waitcnt lgkmcnt(4)
	global_store_dwordx4 v[174:175], v[192:195], off offset:512
	global_store_dwordx4 v[200:201], v[196:199], off offset:512
	s_mov_b64 s[20:21], 0x28000
	v_lshl_add_u64 v[174:175], v[174:175], 0, s[20:21]
	v_lshl_add_u64 v[200:201], v[200:201], 0, s[20:21]
	s_mov_b64 s[20:21], 0x8000
	ds_write_b128 v170, v[50:53]
	ds_write_b128 v171, v[42:45]
	ds_read_b128 v[192:195], v172
	ds_read_b128 v[196:199], v172 offset:1024
	s_waitcnt lgkmcnt(4)
	global_store_dwordx4 v[174:175], v[184:187], off
	global_store_dwordx4 v[200:201], v[188:191], off
	ds_write_b128 v170, v[54:57]
	ds_write_b128 v171, v[46:49]
	ds_read_b128 v[184:187], v172
	ds_read_b128 v[188:191], v172 offset:1024
	s_waitcnt lgkmcnt(4)
	global_store_dwordx4 v[174:175], v[192:195], off offset:512
	global_store_dwordx4 v[200:201], v[196:199], off offset:512
	v_lshl_add_u64 v[174:175], v[174:175], 0, s[20:21]
	v_lshl_add_u64 v[200:201], v[200:201], 0, s[20:21]
	ds_write_b128 v170, v[34:37]
	ds_write_b128 v171, v[26:29]
	ds_read_b128 v[192:195], v172
	ds_read_b128 v[196:199], v172 offset:1024
	s_waitcnt lgkmcnt(4)
	global_store_dwordx4 v[174:175], v[184:187], off
	global_store_dwordx4 v[200:201], v[188:191], off
	ds_write_b128 v170, v[38:41]
	ds_write_b128 v171, v[30:33]
	ds_read_b128 v[184:187], v172
	ds_read_b128 v[188:191], v172 offset:1024
	s_waitcnt lgkmcnt(4)
	global_store_dwordx4 v[174:175], v[192:195], off offset:512
	global_store_dwordx4 v[200:201], v[196:199], off offset:512
	v_lshl_add_u64 v[174:175], v[174:175], 0, s[20:21]
	v_lshl_add_u64 v[200:201], v[200:201], 0, s[20:21]
	ds_write_b128 v170, v[18:21]
	ds_write_b128 v171, v[10:13]
	ds_read_b128 v[192:195], v172
	ds_read_b128 v[196:199], v172 offset:1024
	s_waitcnt lgkmcnt(4)
	global_store_dwordx4 v[174:175], v[184:187], off
	global_store_dwordx4 v[200:201], v[188:191], off
	ds_write_b128 v170, v[22:25]
	ds_write_b128 v171, v[14:17]
	ds_read_b128 v[184:187], v172
	ds_read_b128 v[188:191], v172 offset:1024
	s_waitcnt lgkmcnt(4)
	global_store_dwordx4 v[174:175], v[192:195], off offset:512
	global_store_dwordx4 v[200:201], v[196:199], off offset:512
	v_lshl_add_u64 v[174:175], v[174:175], 0, s[20:21]
	v_lshl_add_u64 v[200:201], v[200:201], 0, s[20:21]
	ds_write_b128 v170, v[6:9]
	ds_write_b128 v171, v[2:5]
	ds_read_b128 v[192:195], v172
	ds_read_b128 v[196:199], v172 offset:1024
	s_waitcnt lgkmcnt(4)
	global_store_dwordx4 v[174:175], v[184:187], off
	global_store_dwordx4 v[200:201], v[188:191], off
	s_waitcnt lgkmcnt(0)
	global_store_dwordx4 v[174:175], v[192:195], off offset:512
	global_store_dwordx4 v[200:201], v[196:199], off offset:512
	s_mov_b64 s[20:21], 0
; __device__ __forceinline__ unsigned cvt_pk_bf16(float lo, float hi) { unsigned r; asm volatile("v_cvt_pk_bf16_f32 %0, %1, %2" : "=v"(r) : "v"(lo), "v"(hi)); return r; }
;     __device__ __forceinline__ void operator()(const pg8::f32x4 (&acc)[2][2][4][2], const Unit& u, int wr, int wc, int fr, int fq) const {
;     ...
;         } else if (u.pn < 8) { const int col0 = u.pn * BM + wc * 32 + 8 * fq;
; #pragma unroll
;             for (int ai = 0; ai < 2; ++ai)
; #pragma unroll
;                 for (int m = 0; m < 4; ++m) { bf16* rowp = PB + (size_t)(row0 + ai * HALF + m * 16) * PBW + col0;
; #pragma unroll
;                     for (int bj = 0; bj < 2; ++bj) { const pg8::f32x4 v0 = acc[ai][bj][m][0], v1 = acc[ai][bj][m][1]; u32x4 w; w.x = cvt_pk_bf16(v0[0], v0[1]); w.y = cvt_pk_bf16(v0[2], v0[3]); w.z = cvt_pk_bf16(v1[0], v1[1]); w.w = cvt_pk_bf16(v1[2], v1[3]);
;                         *(u32x4*)(rowp + bj * HALF) = w; } }
.LBB0_143:
	s_andn2_b64 vcc, exec, s[20:21]
	s_cbranch_vccnz .LBB0_145
	v_or_b32_e32 v138, s13, v158
	v_lshlrev_b64 v[152:153], 12, v[150:151]
	v_lshl_add_u64 v[152:153], s[56:57], 0, v[152:153]
	v_lshlrev_b32_e32 v138, 1, v138
	v_lshl_add_u64 v[152:153], v[152:153], 0, v[138:139]
	v_and_b32_e32 v164, 63, v0
	v_and_b32_e32 v165, 15, v164
	v_lshrrev_b32_e32 v166, 4, v164
	v_lshrrev_b32_e32 v169, 6, v0
	v_lshlrev_b32_e32 v169, 11, v169
	v_add_u32_e32 v169, 0x20000, v169
	v_lshrrev_b32_e32 v167, 2, v164
	v_and_b32_e32 v168, 3, v164
	v_and_b32_e32 v170, 7, v165
	v_xor_b32_e32 v170, v170, v166
	v_lshlrev_b32_e32 v170, 4, v170
	v_lshl_add_u32 v170, v165, 7, v170
	v_add_u32_e32 v170, v169, v170
	v_xor_b32_e32 v171, 64, v170
	v_and_b32_e32 v172, 7, v167
	v_xor_b32_e32 v172, v172, v168
	v_lshlrev_b32_e32 v172, 4, v172
	v_lshl_add_u32 v172, v167, 7, v172
	v_add_u32_e32 v172, v169, v172
	v_xor_b32_e32 v173, 64, v172
	v_sub_u32_e32 v174, v167, v165
	v_lshlrev_b32_e32 v174, 12, v174
	v_sub_u32_e32 v169, v168, v166
	v_lshl_add_u32 v174, v169, 4, v174
	v_ashrrev_i32_e32 v175, 31, v174
	v_lshl_add_u64 v[174:175], v[152:153], 0, v[174:175]
	s_mov_b64 s[20:21], 0x10000
	v_cvt_pk_bf16_f32 v176, v126, v127
	v_cvt_pk_bf16_f32 v177, v128, v129
	v_cvt_pk_bf16_f32 v178, v122, v123
	v_cvt_pk_bf16_f32 v179, v124, v125
	v_cvt_pk_bf16_f32 v180, v118, v119
	v_cvt_pk_bf16_f32 v181, v120, v121
	v_cvt_pk_bf16_f32 v182, v110, v111
	v_cvt_pk_bf16_f32 v183, v112, v113
	ds_write_b128 v170, v[176:179]
	ds_write_b128 v171, v[180:183]
	ds_read_b128 v[184:187], v172
	ds_read_b128 v[188:191], v173
	v_cvt_pk_bf16_f32 v176, v114, v115
	v_cvt_pk_bf16_f32 v177, v116, v117
	v_cvt_pk_bf16_f32 v178, v106, v107
	v_cvt_pk_bf16_f32 v179, v108, v109
	v_cvt_pk_bf16_f32 v180, v98, v99
	v_cvt_pk_bf16_f32 v181, v100, v101
	v_cvt_pk_bf16_f32 v182, v90, v91
	v_cvt_pk_bf16_f32 v183, v92, v93
	ds_write_b128 v170, v[176:179]
	ds_write_b128 v171, v[180:183]
	ds_read_b128 v[192:195], v172
	ds_read_b128 v[196:199], v173
	s_waitcnt lgkmcnt(4)
	global_store_dwordx4 v[174:175], v[184:187], off
	global_store_dwordx4 v[174:175], v[188:191], off offset:256
	v_lshl_add_u64 v[174:175], v[174:175], 0, s[20:21]
	v_cvt_pk_bf16_f32 v176, v102, v103
	v_cvt_pk_bf16_f32 v177, v104, v105
	v_cvt_pk_bf16_f32 v178, v94, v95
	v_cvt_pk_bf16_f32 v179, v96, v97
	v_cvt_pk_bf16_f32 v180, v82, v83
	v_cvt_pk_bf16_f32 v181, v84, v85
	v_cvt_pk_bf16_f32 v182, v74, v75
	v_cvt_pk_bf16_f32 v183, v76, v77
	ds_write_b128 v170, v[176:179]
	ds_write_b128 v171, v[180:183]
	ds_read_b128 v[184:187], v172
	ds_read_b128 v[188:191], v173
	s_waitcnt lgkmcnt(4)
	global_store_dwordx4 v[174:175], v[192:195], off
	global_store_dwordx4 v[174:175], v[196:199], off offset:256
	v_lshl_add_u64 v[174:175], v[174:175], 0, s[20:21]
	v_cvt_pk_bf16_f32 v176, v86, v87
	v_cvt_pk_bf16_f32 v177, v88, v89
	v_cvt_pk_bf16_f32 v178, v78, v79
	v_cvt_pk_bf16_f32 v179, v80, v81
	v_cvt_pk_bf16_f32 v180, v70, v71
	v_cvt_pk_bf16_f32 v181, v72, v73
	v_cvt_pk_bf16_f32 v182, v66, v67
	v_cvt_pk_bf16_f32 v183, v68, v69
	ds_write_b128 v170, v[176:179]
	ds_write_b128 v171, v[180:183]
	ds_read_b128 v[192:195], v172
	ds_read_b128 v[196:199], v173
	s_waitcnt lgkmcnt(4)
	global_store_dwordx4 v[174:175], v[184:187], off
	global_store_dwordx4 v[174:175], v[188:191], off offset:256
	v_lshl_add_u64 v[174:175], v[174:175], 0, s[20:21]
	v_cvt_pk_bf16_f32 v176, v62, v63
	v_cvt_pk_bf16_f32 v177, v64, v65
	v_cvt_pk_bf16_f32 v178, v58, v59
	v_cvt_pk_bf16_f32 v179, v60, v61
	v_cvt_pk_bf16_f32 v180, v50, v51
	v_cvt_pk_bf16_f32 v181, v52, v53
	v_cvt_pk_bf16_f32 v182, v42, v43
	v_cvt_pk_bf16_f32 v183, v44, v45
	ds_write_b128 v170, v[176:179]
	ds_write_b128 v171, v[180:183]
	ds_read_b128 v[184:187], v172
	ds_read_b128 v[188:191], v173
	s_waitcnt lgkmcnt(4)
	global_store_dwordx4 v[174:175], v[192:195], off
	global_store_dwordx4 v[174:175], v[196:199], off offset:256
	s_mov_b64 s[20:21], 0x50000
	v_lshl_add_u64 v[174:175], v[174:175], 0, s[20:21]
	s_mov_b64 s[20:21], 0x10000
	v_cvt_pk_bf16_f32 v176, v54, v55
	v_cvt_pk_bf16_f32 v177, v56, v57
	v_cvt_pk_bf16_f32 v178, v46, v47
	v_cvt_pk_bf16_f32 v179, v48, v49
	v_cvt_pk_bf16_f32 v180, v34, v35
	v_cvt_pk_bf16_f32 v181, v36, v37
	v_cvt_pk_bf16_f32 v182, v26, v27
	v_cvt_pk_bf16_f32 v183, v28, v29
	ds_write_b128 v170, v[176:179]
	ds_write_b128 v171, v[180:183]
	ds_read_b128 v[192:195], v172
	ds_read_b128 v[196:199], v173
	s_waitcnt lgkmcnt(4)
	global_store_dwordx4 v[174:175], v[184:187], off
	global_store_dwordx4 v[174:175], v[188:191], off offset:256
	v_lshl_add_u64 v[174:175], v[174:175], 0, s[20:21]
	v_cvt_pk_bf16_f32 v176, v38, v39
	v_cvt_pk_bf16_f32 v177, v40, v41
	v_cvt_pk_bf16_f32 v178, v30, v31
	v_cvt_pk_bf16_f32 v179, v32, v33
	v_cvt_pk_bf16_f32 v180, v18, v19
	v_cvt_pk_bf16_f32 v181, v20, v21
	v_cvt_pk_bf16_f32 v182, v10, v11
	v_cvt_pk_bf16_f32 v183, v12, v13
	ds_write_b128 v170, v[176:179]
	ds_write_b128 v171, v[180:183]
	ds_read_b128 v[184:187], v172
	ds_read_b128 v[188:191], v173
	s_waitcnt lgkmcnt(4)
	global_store_dwordx4 v[174:175], v[192:195], off
	global_store_dwordx4 v[174:175], v[196:199], off offset:256
	v_lshl_add_u64 v[174:175], v[174:175], 0, s[20:21]
	v_cvt_pk_bf16_f32 v176, v22, v23
	v_cvt_pk_bf16_f32 v177, v24, v25
	v_cvt_pk_bf16_f32 v178, v14, v15
	v_cvt_pk_bf16_f32 v179, v16, v17
	v_cvt_pk_bf16_f32 v180, v6, v7
	v_cvt_pk_bf16_f32 v181, v8, v9
	v_cvt_pk_bf16_f32 v182, v2, v3
	v_cvt_pk_bf16_f32 v183, v4, v5
	ds_write_b128 v170, v[176:179]
	ds_write_b128 v171, v[180:183]
	ds_read_b128 v[192:195], v172
	ds_read_b128 v[196:199], v173
	s_waitcnt lgkmcnt(4)
	global_store_dwordx4 v[174:175], v[184:187], off
	global_store_dwordx4 v[174:175], v[188:191], off offset:256
	v_lshl_add_u64 v[174:175], v[174:175], 0, s[20:21]
	s_waitcnt lgkmcnt(0)
	global_store_dwordx4 v[174:175], v[192:195], off
	global_store_dwordx4 v[174:175], v[196:199], off offset:256
